# hyena-lat Toeplitz loop rewritten: linear LDS addressing, 7 fixed-tile segments, aligned dword reads for the Toeplitz fragment instead of an unaligned ds_read_b128
# speedup vs baseline: 1.2091x; 1.0376x over previous
.LBB0_619:
	s_or_b64 exec, exec, s[28:29]
	s_waitcnt vmcnt(1)
	v_lshlrev_b32_e32 v41, 16, v5
	v_and_b32_e32 v43, 0xffff0000, v5
	s_waitcnt vmcnt(0)
	v_and_b32_e32 v44, 0xffff0000, v8
	v_lshlrev_b32_e32 v5, 16, v8
	v_and_b32_e32 v8, 0xffff0000, v2
	v_lshlrev_b32_e32 v30, 16, v6
	v_and_b32_e32 v6, 0xffff0000, v6
	v_mov_b32_e32 v36, v8
	v_lshrrev_b32_e32 v233, 5, v0
	v_lshlrev_b32_e32 v0, 16, v2
	v_lshlrev_b32_e32 v45, 16, v9
	v_and_b32_e32 v47, 0xffff0000, v9
	v_and_b32_e32 v48, 0xffff0000, v3
	v_lshlrev_b32_e32 v9, 16, v3
	v_pk_mul_f32 v[2:3], v[20:21], v[36:37]
	v_mov_b32_e32 v38, v6
	v_and_b32_e32 v31, 31, v111
	v_pk_fma_f32 v[2:3], v[20:21], v[0:1], v[2:3] op_sel:[0,0,1] op_sel_hi:[1,0,0]
	v_pk_mul_f32 v[20:21], v[18:19], v[38:39]
	v_and_b32_e32 v40, 0xffff0000, v4
	v_lshlrev_b32_e32 v49, 16, v4
	v_and_b32_e32 v4, 0xffff0000, v7
	v_lshlrev_b32_e32 v7, 16, v7
	v_pk_fma_f32 v[18:19], v[18:19], v[30:31], v[20:21] op_sel:[0,0,1] op_sel_hi:[1,0,0]
	v_pk_fma_f32 v[2:3], v[12:13], v[8:9], v[2:3]
	v_pk_fma_f32 v[18:19], v[10:11], v[6:7], v[18:19]
	v_pk_add_f32 v[2:3], v[16:17], v[2:3]
	v_pk_add_f32 v[18:19], v[14:15], v[18:19]
	v_mov_b32_e32 v42, v41
	v_pk_mul_f32 v[2:3], v[2:3], v[18:19]
	v_pk_mov_b32 v[18:19], v[8:9], v[48:49] op_sel:[1,0]
	v_cvt_pk_bf16_f32 v2, v2, v3
	v_pk_mul_f32 v[18:19], v[28:29], v[18:19]
	v_mov_b32_e32 v46, v45
	v_pk_fma_f32 v[8:9], v[24:25], v[8:9], v[18:19]
	v_pk_mov_b32 v[18:19], v[6:7], v[4:5] op_sel:[1,0]
	v_pk_fma_f32 v[8:9], v[12:13], v[48:49], v[8:9]
	v_pk_mul_f32 v[18:19], v[26:27], v[18:19]
	v_pk_add_f32 v[8:9], v[16:17], v[8:9]
	v_pk_fma_f32 v[6:7], v[22:23], v[6:7], v[18:19]
	v_mov_b32_e32 v34, v43
	v_pk_fma_f32 v[6:7], v[10:11], v[4:5], v[6:7]
	v_mov_b32_e32 v32, v47
	v_pk_add_f32 v[6:7], v[14:15], v[6:7]
	v_add_u32_e32 v0, 0x400, v223
	v_pk_mul_f32 v[6:7], v[8:9], v[6:7]
	v_pk_mov_b32 v[8:9], v[4:5], v[44:45] op_sel:[1,0]
	v_cvt_pk_bf16_f32 v3, v6, v7
	v_pk_mov_b32 v[6:7], v[48:49], v[40:41] op_sel:[1,0]
	v_pk_mul_f32 v[8:9], v[26:27], v[8:9]
	v_pk_mul_f32 v[6:7], v[28:29], v[6:7]
	v_pk_fma_f32 v[4:5], v[22:23], v[4:5], v[8:9]
	v_pk_fma_f32 v[6:7], v[24:25], v[48:49], v[6:7]
	v_pk_fma_f32 v[4:5], v[10:11], v[44:45], v[4:5]
	v_pk_fma_f32 v[6:7], v[12:13], v[40:41], v[6:7]
	v_pk_add_f32 v[4:5], v[14:15], v[4:5]
	v_pk_add_f32 v[6:7], v[16:17], v[6:7]
	v_pk_mul_f32 v[8:9], v[26:27], v[46:47]
	v_pk_mul_f32 v[4:5], v[6:7], v[4:5]
	v_pk_mul_f32 v[6:7], v[28:29], v[42:43]
	v_pk_fma_f32 v[8:9], v[22:23], v[44:45], v[8:9]
	v_pk_fma_f32 v[6:7], v[24:25], v[40:41], v[6:7]
	v_pk_fma_f32 v[8:9], v[10:11], v[32:33], v[8:9]
	v_pk_fma_f32 v[6:7], v[12:13], v[34:35], v[6:7]
	v_pk_add_f32 v[8:9], v[14:15], v[8:9]
	v_pk_add_f32 v[6:7], v[16:17], v[6:7]
	v_ashrrev_i32_e32 v0, 1, v0
	v_pk_mul_f32 v[6:7], v[6:7], v[8:9]
	v_cvt_pk_bf16_f32 v4, v4, v5
	v_cvt_pk_bf16_f32 v5, v6, v7
	v_mul_i32_i24_e32 v6, 0x3c00, v222
	v_lshlrev_b32_e32 v226, 1, v223
	v_and_b32_e32 v0, -16, v0
	v_add3_u32 v0, v6, v226, v0
	ds_write_b128 v0, v[2:5] offset:18560
	v_lshlrev_b32_e32 v235, 1, v31
	v_lshlrev_b32_e32 v5, 4, v233
	v_xad_u32 v2, v5, 16, v235
	s_waitcnt lgkmcnt(0)
	s_barrier
	v_lshlrev_b32_e32 v0, 3, v233
	ds_read_b32 v6, v2 offset:14
	v_or_b32_e32 v2, 7, v0
	v_lshlrev_b32_e32 v234, 5, v31
	v_sub_u32_e32 v2, v31, v2
	v_or_b32_e32 v0, v234, v0
	v_lshlrev_b32_e32 v2, 1, v2
	s_movk_i32 s0, 0x1e00
	v_add_u16_e32 v8, 0x13f0, v0
	ds_read_b96 v[2:4], v2 offset:32
	ds_read_b128 v[66:69], v1 offset:16512
	v_mul_lo_u32 v236, v159, s0
	v_lshrrev_b16_e32 v8, 1, v8
	s_waitcnt lgkmcnt(2)
	v_alignbit_b32 v94, v6, v6, 16
	v_lshlrev_b32_e32 v6, 1, v0
	v_lshlrev_b32_e32 v7, 1, v236
	v_and_b32_e32 v8, 0x7ff0, v8
	v_add3_u32 v6, v6, v7, v8
	ds_read_b128 v[70:73], v6 offset:26720
	s_waitcnt lgkmcnt(2)
	v_alignbit_b32 v97, v2, v2, 16
	v_sub_u32_e32 v2, v235, v5
	v_mov_b32_e32 v14, v1
	v_mov_b32_e32 v15, v1
	v_alignbit_b32 v95, v4, v4, 16
	v_alignbit_b32 v96, v3, v3, 16
	v_add_u32_e32 v237, 50, v2
	v_add_u32_e32 v238, 0x13d0, v0
	v_mov_b32_e32 v0, v1
	v_mov_b32_e32 v2, v1
	v_mov_b32_e32 v3, v1
	v_mov_b32_e32 v4, v1
	v_mov_b32_e32 v5, v1
	v_mov_b32_e32 v6, v1
	v_mov_b32_e32 v7, v1
	v_mov_b32_e32 v8, v1
	v_mov_b32_e32 v9, v1
	v_mov_b32_e32 v10, v1
	v_mov_b32_e32 v11, v1
	v_mov_b32_e32 v12, v1
	v_mov_b32_e32 v13, v1
	v_mov_b64_e32 v[64:65], v[14:15]
	v_mov_b64_e32 v[48:49], v[14:15]
	v_mov_b64_e32 v[32:33], v[14:15]
	s_waitcnt lgkmcnt(1)
	v_mov_b64_e32 v[80:81], v[68:69]
	v_mov_b64_e32 v[76:77], v[68:69]
	v_mov_b64_e32 v[62:63], v[12:13]
	v_mov_b64_e32 v[60:61], v[10:11]
	v_mov_b64_e32 v[58:59], v[8:9]
	v_mov_b64_e32 v[56:57], v[6:7]
	v_mov_b64_e32 v[54:55], v[4:5]
	v_mov_b64_e32 v[52:53], v[2:3]
	v_mov_b64_e32 v[50:51], v[0:1]
	v_mov_b64_e32 v[46:47], v[12:13]
	v_mov_b64_e32 v[44:45], v[10:11]
	v_mov_b64_e32 v[42:43], v[8:9]
	v_mov_b64_e32 v[40:41], v[6:7]
	v_mov_b64_e32 v[38:39], v[4:5]
	v_mov_b64_e32 v[36:37], v[2:3]
	v_mov_b64_e32 v[34:35], v[0:1]
	v_mov_b64_e32 v[30:31], v[12:13]
	v_mov_b64_e32 v[28:29], v[10:11]
	v_mov_b64_e32 v[26:27], v[8:9]
	v_mov_b64_e32 v[24:25], v[6:7]
	v_mov_b64_e32 v[22:23], v[4:5]
	v_mov_b64_e32 v[20:21], v[2:3]
	v_mov_b64_e32 v[18:19], v[0:1]
	v_mov_b64_e32 v[16:17], v[14:15]
	s_movk_i32 s5, 0xfeff
	v_mov_b64_e32 v[78:79], v[66:67]
	v_mov_b64_e32 v[74:75], v[66:67]
	v_mov_b64_e32 v[14:15], v[12:13]
	v_mov_b64_e32 v[12:13], v[10:11]
	v_mov_b64_e32 v[10:11], v[8:9]
	v_mov_b64_e32 v[8:9], v[6:7]
	v_mov_b64_e32 v[6:7], v[4:5]
	v_mov_b64_e32 v[4:5], v[2:3]
	v_mov_b64_e32 v[2:3], v[0:1]
	s_waitcnt lgkmcnt(0)
	v_and_b32_e32 v248, 31, v151
	v_bfe_u32 v245, v151, 5, 1
	v_lshrrev_b32_e32 v247, 6, v151
	v_lshlrev_b32_e32 v244, 3, v245
	v_sub_u32_e32 v244, v248, v244
	v_add_u32_e32 v244, 9, v244
	v_and_b32_e32 v249, 1, v244
	v_cmp_eq_u32_e32 vcc, 1, v249
	v_lshrrev_b32_e32 v244, 1, v244
	v_lshlrev_b32_e32 v244, 2, v244
	s_mov_b32 s5, 0xffff
	v_mul_u32_u24_e32 v246, 80, v248
	v_lshl_add_u32 v246, v245, 4, v246
	v_mul_u32_u24_e32 v247, 0x3c00, v247
	v_add_u32_e32 v247, v246, v247
	v_add_u32_e32 v247, 0x7230, v247
	v_add_u32_e32 v246, 32, v247
	v_add_u32_e32 v245, 32, v244
	ds_read2_b32 v[66:67], v244 offset1:1
	ds_read2_b32 v[68:69], v244 offset0:2 offset1:3
	ds_read_b32 v70, v244 offset:16
	ds_read_b128 v[76:79], v246 offset:0
	v_add_u32_e32 v244, 64, v244
	v_add_u32_e32 v246, 0xffffffb0, v246
	ds_read2_b32 v[92:93], v245 offset1:1
	ds_read2_b32 v[94:95], v245 offset0:2 offset1:3
	ds_read_b32 v96, v245 offset:16
	ds_read_b128 v[102:105], v247 offset:0
	v_add_u32_e32 v245, 64, v245
	v_add_u32_e32 v247, 0xffffffb0, v247
	s_mov_b32 s4, 31
.Lhy_seg0:
	s_waitcnt lgkmcnt(4)
	v_alignbit_b32 v72, v69, v69, 16
	v_bfi_b32 v249, s5, v70, v69
	v_cndmask_b32_e32 v72, v72, v249, vcc
	v_alignbit_b32 v73, v68, v68, 16
	v_bfi_b32 v249, s5, v69, v68
	v_cndmask_b32_e32 v73, v73, v249, vcc
	v_alignbit_b32 v74, v67, v67, 16
	v_bfi_b32 v249, s5, v68, v67
	v_cndmask_b32_e32 v74, v74, v249, vcc
	v_alignbit_b32 v75, v66, v66, 16
	v_bfi_b32 v249, s5, v67, v66
	v_cndmask_b32_e32 v75, v75, v249, vcc
	s_nop 1
	v_mfma_f32_32x32x16_bf16 v[50:65], v[72:75], v[76:79], v[50:65]
	ds_read2_b32 v[66:67], v244 offset1:1
	ds_read2_b32 v[68:69], v244 offset0:2 offset1:3
	ds_read_b32 v70, v244 offset:16
	ds_read_b128 v[76:79], v246 offset:0
	v_add_u32_e32 v244, 64, v244
	v_add_u32_e32 v246, 0xffffffb0, v246
	s_waitcnt lgkmcnt(4)
	v_alignbit_b32 v98, v95, v95, 16
	v_bfi_b32 v249, s5, v96, v95
	v_cndmask_b32_e32 v98, v98, v249, vcc
	v_alignbit_b32 v99, v94, v94, 16
	v_bfi_b32 v249, s5, v95, v94
	v_cndmask_b32_e32 v99, v99, v249, vcc
	v_alignbit_b32 v100, v93, v93, 16
	v_bfi_b32 v249, s5, v94, v93
	v_cndmask_b32_e32 v100, v100, v249, vcc
	v_alignbit_b32 v101, v92, v92, 16
	v_bfi_b32 v249, s5, v93, v92
	v_cndmask_b32_e32 v101, v101, v249, vcc
	s_nop 1
	v_mfma_f32_32x32x16_bf16 v[50:65], v[98:101], v[102:105], v[50:65]
	ds_read2_b32 v[92:93], v245 offset1:1
	ds_read2_b32 v[94:95], v245 offset0:2 offset1:3
	ds_read_b32 v96, v245 offset:16
	ds_read_b128 v[102:105], v247 offset:0
	v_add_u32_e32 v245, 64, v245
	v_add_u32_e32 v247, 0xffffffb0, v247
	s_add_i32 s4, s4, -1
	s_cmp_lg_u32 s4, 0
	s_cbranch_scc1 .Lhy_seg0
	s_waitcnt lgkmcnt(4)
	v_alignbit_b32 v72, v69, v69, 16
	v_bfi_b32 v249, s5, v70, v69
	v_cndmask_b32_e32 v72, v72, v249, vcc
	v_alignbit_b32 v73, v68, v68, 16
	v_bfi_b32 v249, s5, v69, v68
	v_cndmask_b32_e32 v73, v73, v249, vcc
	v_alignbit_b32 v74, v67, v67, 16
	v_bfi_b32 v249, s5, v68, v67
	v_cndmask_b32_e32 v74, v74, v249, vcc
	v_alignbit_b32 v75, v66, v66, 16
	v_bfi_b32 v249, s5, v67, v66
	v_cndmask_b32_e32 v75, v75, v249, vcc
	s_nop 1
	v_mfma_f32_32x32x16_bf16 v[50:65], v[72:75], v[76:79], v[50:65]
	s_waitcnt lgkmcnt(0)
	v_alignbit_b32 v98, v95, v95, 16
	v_bfi_b32 v249, s5, v96, v95
	v_cndmask_b32_e32 v98, v98, v249, vcc
	v_alignbit_b32 v99, v94, v94, 16
	v_bfi_b32 v249, s5, v95, v94
	v_cndmask_b32_e32 v99, v99, v249, vcc
	v_alignbit_b32 v100, v93, v93, 16
	v_bfi_b32 v249, s5, v94, v93
	v_cndmask_b32_e32 v100, v100, v249, vcc
	v_alignbit_b32 v101, v92, v92, 16
	v_bfi_b32 v249, s5, v93, v92
	v_cndmask_b32_e32 v101, v101, v249, vcc
	s_nop 1
	v_mfma_f32_32x32x16_bf16 v[50:65], v[98:101], v[102:105], v[50:65]
	ds_read2_b32 v[66:67], v244 offset1:1
	ds_read2_b32 v[68:69], v244 offset0:2 offset1:3
	ds_read_b32 v70, v244 offset:16
	ds_read_b128 v[76:79], v246 offset:0
	ds_read_b128 v[80:83], v246 offset:2560
	v_add_u32_e32 v244, 64, v244
	v_add_u32_e32 v246, 0xffffffb0, v246
	ds_read2_b32 v[92:93], v245 offset1:1
	ds_read2_b32 v[94:95], v245 offset0:2 offset1:3
	ds_read_b32 v96, v245 offset:16
	ds_read_b128 v[102:105], v247 offset:0
	ds_read_b128 v[106:109], v247 offset:2560
	v_add_u32_e32 v245, 64, v245
	v_add_u32_e32 v247, 0xffffffb0, v247
	s_mov_b32 s4, 31
.Lhy_seg1:
	s_waitcnt lgkmcnt(5)
	v_alignbit_b32 v72, v69, v69, 16
	v_bfi_b32 v249, s5, v70, v69
	v_cndmask_b32_e32 v72, v72, v249, vcc
	v_alignbit_b32 v73, v68, v68, 16
	v_bfi_b32 v249, s5, v69, v68
	v_cndmask_b32_e32 v73, v73, v249, vcc
	v_alignbit_b32 v74, v67, v67, 16
	v_bfi_b32 v249, s5, v68, v67
	v_cndmask_b32_e32 v74, v74, v249, vcc
	v_alignbit_b32 v75, v66, v66, 16
	v_bfi_b32 v249, s5, v67, v66
	v_cndmask_b32_e32 v75, v75, v249, vcc
	s_nop 1
	v_mfma_f32_32x32x16_bf16 v[50:65], v[72:75], v[76:79], v[50:65]
	v_mfma_f32_32x32x16_bf16 v[34:49], v[72:75], v[80:83], v[34:49]
	ds_read2_b32 v[66:67], v244 offset1:1
	ds_read2_b32 v[68:69], v244 offset0:2 offset1:3
	ds_read_b32 v70, v244 offset:16
	ds_read_b128 v[76:79], v246 offset:0
	ds_read_b128 v[80:83], v246 offset:2560
	v_add_u32_e32 v244, 64, v244
	v_add_u32_e32 v246, 0xffffffb0, v246
	s_waitcnt lgkmcnt(5)
	v_alignbit_b32 v98, v95, v95, 16
	v_bfi_b32 v249, s5, v96, v95
	v_cndmask_b32_e32 v98, v98, v249, vcc
	v_alignbit_b32 v99, v94, v94, 16
	v_bfi_b32 v249, s5, v95, v94
	v_cndmask_b32_e32 v99, v99, v249, vcc
	v_alignbit_b32 v100, v93, v93, 16
	v_bfi_b32 v249, s5, v94, v93
	v_cndmask_b32_e32 v100, v100, v249, vcc
	v_alignbit_b32 v101, v92, v92, 16
	v_bfi_b32 v249, s5, v93, v92
	v_cndmask_b32_e32 v101, v101, v249, vcc
	s_nop 1
	v_mfma_f32_32x32x16_bf16 v[50:65], v[98:101], v[102:105], v[50:65]
	v_mfma_f32_32x32x16_bf16 v[34:49], v[98:101], v[106:109], v[34:49]
	ds_read2_b32 v[92:93], v245 offset1:1
	ds_read2_b32 v[94:95], v245 offset0:2 offset1:3
	ds_read_b32 v96, v245 offset:16
	ds_read_b128 v[102:105], v247 offset:0
	ds_read_b128 v[106:109], v247 offset:2560
	v_add_u32_e32 v245, 64, v245
	v_add_u32_e32 v247, 0xffffffb0, v247
	s_add_i32 s4, s4, -1
	s_cmp_lg_u32 s4, 0
	s_cbranch_scc1 .Lhy_seg1
	s_waitcnt lgkmcnt(5)
	v_alignbit_b32 v72, v69, v69, 16
	v_bfi_b32 v249, s5, v70, v69
	v_cndmask_b32_e32 v72, v72, v249, vcc
	v_alignbit_b32 v73, v68, v68, 16
	v_bfi_b32 v249, s5, v69, v68
	v_cndmask_b32_e32 v73, v73, v249, vcc
	v_alignbit_b32 v74, v67, v67, 16
	v_bfi_b32 v249, s5, v68, v67
	v_cndmask_b32_e32 v74, v74, v249, vcc
	v_alignbit_b32 v75, v66, v66, 16
	v_bfi_b32 v249, s5, v67, v66
	v_cndmask_b32_e32 v75, v75, v249, vcc
	s_nop 1
	v_mfma_f32_32x32x16_bf16 v[50:65], v[72:75], v[76:79], v[50:65]
	v_mfma_f32_32x32x16_bf16 v[34:49], v[72:75], v[80:83], v[34:49]
	s_waitcnt lgkmcnt(0)
	v_alignbit_b32 v98, v95, v95, 16
	v_bfi_b32 v249, s5, v96, v95
	v_cndmask_b32_e32 v98, v98, v249, vcc
	v_alignbit_b32 v99, v94, v94, 16
	v_bfi_b32 v249, s5, v95, v94
	v_cndmask_b32_e32 v99, v99, v249, vcc
	v_alignbit_b32 v100, v93, v93, 16
	v_bfi_b32 v249, s5, v94, v93
	v_cndmask_b32_e32 v100, v100, v249, vcc
	v_alignbit_b32 v101, v92, v92, 16
	v_bfi_b32 v249, s5, v93, v92
	v_cndmask_b32_e32 v101, v101, v249, vcc
	s_nop 1
	v_mfma_f32_32x32x16_bf16 v[50:65], v[98:101], v[102:105], v[50:65]
	v_mfma_f32_32x32x16_bf16 v[34:49], v[98:101], v[106:109], v[34:49]
	ds_read2_b32 v[66:67], v244 offset1:1
	ds_read2_b32 v[68:69], v244 offset0:2 offset1:3
	ds_read_b32 v70, v244 offset:16
	ds_read_b128 v[76:79], v246 offset:0
	ds_read_b128 v[80:83], v246 offset:2560
	ds_read_b128 v[84:87], v246 offset:5120
	v_add_u32_e32 v244, 64, v244
	v_add_u32_e32 v246, 0xffffffb0, v246
	ds_read2_b32 v[92:93], v245 offset1:1
	ds_read2_b32 v[94:95], v245 offset0:2 offset1:3
	ds_read_b32 v96, v245 offset:16
	ds_read_b128 v[102:105], v247 offset:0
	ds_read_b128 v[106:109], v247 offset:2560
	ds_read_b128 v[236:239], v247 offset:5120
	v_add_u32_e32 v245, 64, v245
	v_add_u32_e32 v247, 0xffffffb0, v247
	s_mov_b32 s4, 31
.Lhy_seg2:
	s_waitcnt lgkmcnt(6)
	v_alignbit_b32 v72, v69, v69, 16
	v_bfi_b32 v249, s5, v70, v69
	v_cndmask_b32_e32 v72, v72, v249, vcc
	v_alignbit_b32 v73, v68, v68, 16
	v_bfi_b32 v249, s5, v69, v68
	v_cndmask_b32_e32 v73, v73, v249, vcc
	v_alignbit_b32 v74, v67, v67, 16
	v_bfi_b32 v249, s5, v68, v67
	v_cndmask_b32_e32 v74, v74, v249, vcc
	v_alignbit_b32 v75, v66, v66, 16
	v_bfi_b32 v249, s5, v67, v66
	v_cndmask_b32_e32 v75, v75, v249, vcc
	s_nop 1
	v_mfma_f32_32x32x16_bf16 v[50:65], v[72:75], v[76:79], v[50:65]
	v_mfma_f32_32x32x16_bf16 v[34:49], v[72:75], v[80:83], v[34:49]
	v_mfma_f32_32x32x16_bf16 v[18:33], v[72:75], v[84:87], v[18:33]
	ds_read2_b32 v[66:67], v244 offset1:1
	ds_read2_b32 v[68:69], v244 offset0:2 offset1:3
	ds_read_b32 v70, v244 offset:16
	ds_read_b128 v[76:79], v246 offset:0
	ds_read_b128 v[80:83], v246 offset:2560
	ds_read_b128 v[84:87], v246 offset:5120
	v_add_u32_e32 v244, 64, v244
	v_add_u32_e32 v246, 0xffffffb0, v246
	s_waitcnt lgkmcnt(6)
	v_alignbit_b32 v98, v95, v95, 16
	v_bfi_b32 v249, s5, v96, v95
	v_cndmask_b32_e32 v98, v98, v249, vcc
	v_alignbit_b32 v99, v94, v94, 16
	v_bfi_b32 v249, s5, v95, v94
	v_cndmask_b32_e32 v99, v99, v249, vcc
	v_alignbit_b32 v100, v93, v93, 16
	v_bfi_b32 v249, s5, v94, v93
	v_cndmask_b32_e32 v100, v100, v249, vcc
	v_alignbit_b32 v101, v92, v92, 16
	v_bfi_b32 v249, s5, v93, v92
	v_cndmask_b32_e32 v101, v101, v249, vcc
	s_nop 1
	v_mfma_f32_32x32x16_bf16 v[50:65], v[98:101], v[102:105], v[50:65]
	v_mfma_f32_32x32x16_bf16 v[34:49], v[98:101], v[106:109], v[34:49]
	v_mfma_f32_32x32x16_bf16 v[18:33], v[98:101], v[236:239], v[18:33]
	ds_read2_b32 v[92:93], v245 offset1:1
	ds_read2_b32 v[94:95], v245 offset0:2 offset1:3
	ds_read_b32 v96, v245 offset:16
	ds_read_b128 v[102:105], v247 offset:0
	ds_read_b128 v[106:109], v247 offset:2560
	ds_read_b128 v[236:239], v247 offset:5120
	v_add_u32_e32 v245, 64, v245
	v_add_u32_e32 v247, 0xffffffb0, v247
	s_add_i32 s4, s4, -1
	s_cmp_lg_u32 s4, 0
	s_cbranch_scc1 .Lhy_seg2
	s_waitcnt lgkmcnt(6)
	v_alignbit_b32 v72, v69, v69, 16
	v_bfi_b32 v249, s5, v70, v69
	v_cndmask_b32_e32 v72, v72, v249, vcc
	v_alignbit_b32 v73, v68, v68, 16
	v_bfi_b32 v249, s5, v69, v68
	v_cndmask_b32_e32 v73, v73, v249, vcc
	v_alignbit_b32 v74, v67, v67, 16
	v_bfi_b32 v249, s5, v68, v67
	v_cndmask_b32_e32 v74, v74, v249, vcc
	v_alignbit_b32 v75, v66, v66, 16
	v_bfi_b32 v249, s5, v67, v66
	v_cndmask_b32_e32 v75, v75, v249, vcc
	s_nop 1
	v_mfma_f32_32x32x16_bf16 v[50:65], v[72:75], v[76:79], v[50:65]
	v_mfma_f32_32x32x16_bf16 v[34:49], v[72:75], v[80:83], v[34:49]
	v_mfma_f32_32x32x16_bf16 v[18:33], v[72:75], v[84:87], v[18:33]
	s_waitcnt lgkmcnt(0)
	v_alignbit_b32 v98, v95, v95, 16
	v_bfi_b32 v249, s5, v96, v95
	v_cndmask_b32_e32 v98, v98, v249, vcc
	v_alignbit_b32 v99, v94, v94, 16
	v_bfi_b32 v249, s5, v95, v94
	v_cndmask_b32_e32 v99, v99, v249, vcc
	v_alignbit_b32 v100, v93, v93, 16
	v_bfi_b32 v249, s5, v94, v93
	v_cndmask_b32_e32 v100, v100, v249, vcc
	v_alignbit_b32 v101, v92, v92, 16
	v_bfi_b32 v249, s5, v93, v92
	v_cndmask_b32_e32 v101, v101, v249, vcc
	s_nop 1
	v_mfma_f32_32x32x16_bf16 v[50:65], v[98:101], v[102:105], v[50:65]
	v_mfma_f32_32x32x16_bf16 v[34:49], v[98:101], v[106:109], v[34:49]
	v_mfma_f32_32x32x16_bf16 v[18:33], v[98:101], v[236:239], v[18:33]
	ds_read2_b32 v[66:67], v244 offset1:1
	ds_read2_b32 v[68:69], v244 offset0:2 offset1:3
	ds_read_b32 v70, v244 offset:16
	ds_read_b128 v[76:79], v246 offset:0
	ds_read_b128 v[80:83], v246 offset:2560
	ds_read_b128 v[84:87], v246 offset:5120
	ds_read_b128 v[88:91], v246 offset:7680
	v_add_u32_e32 v244, 64, v244
	v_add_u32_e32 v246, 0xffffffb0, v246
	ds_read2_b32 v[92:93], v245 offset1:1
	ds_read2_b32 v[94:95], v245 offset0:2 offset1:3
	ds_read_b32 v96, v245 offset:16
	ds_read_b128 v[102:105], v247 offset:0
	ds_read_b128 v[106:109], v247 offset:2560
	ds_read_b128 v[236:239], v247 offset:5120
	ds_read_b128 v[240:243], v247 offset:7680
	v_add_u32_e32 v245, 64, v245
	v_add_u32_e32 v247, 0xffffffb0, v247
	s_mov_b32 s4, 62
.Lhy_seg3:
	s_waitcnt lgkmcnt(7)
	v_alignbit_b32 v72, v69, v69, 16
	v_bfi_b32 v249, s5, v70, v69
	v_cndmask_b32_e32 v72, v72, v249, vcc
	v_alignbit_b32 v73, v68, v68, 16
	v_bfi_b32 v249, s5, v69, v68
	v_cndmask_b32_e32 v73, v73, v249, vcc
	v_alignbit_b32 v74, v67, v67, 16
	v_bfi_b32 v249, s5, v68, v67
	v_cndmask_b32_e32 v74, v74, v249, vcc
	v_alignbit_b32 v75, v66, v66, 16
	v_bfi_b32 v249, s5, v67, v66
	v_cndmask_b32_e32 v75, v75, v249, vcc
	s_nop 1
	v_mfma_f32_32x32x16_bf16 v[50:65], v[72:75], v[76:79], v[50:65]
	v_mfma_f32_32x32x16_bf16 v[34:49], v[72:75], v[80:83], v[34:49]
	v_mfma_f32_32x32x16_bf16 v[18:33], v[72:75], v[84:87], v[18:33]
	v_mfma_f32_32x32x16_bf16 v[2:17], v[72:75], v[88:91], v[2:17]
	ds_read2_b32 v[66:67], v244 offset1:1
	ds_read2_b32 v[68:69], v244 offset0:2 offset1:3
	ds_read_b32 v70, v244 offset:16
	ds_read_b128 v[76:79], v246 offset:0
	ds_read_b128 v[80:83], v246 offset:2560
	ds_read_b128 v[84:87], v246 offset:5120
	ds_read_b128 v[88:91], v246 offset:7680
	v_add_u32_e32 v244, 64, v244
	v_add_u32_e32 v246, 0xffffffb0, v246
	s_waitcnt lgkmcnt(7)
	v_alignbit_b32 v98, v95, v95, 16
	v_bfi_b32 v249, s5, v96, v95
	v_cndmask_b32_e32 v98, v98, v249, vcc
	v_alignbit_b32 v99, v94, v94, 16
	v_bfi_b32 v249, s5, v95, v94
	v_cndmask_b32_e32 v99, v99, v249, vcc
	v_alignbit_b32 v100, v93, v93, 16
	v_bfi_b32 v249, s5, v94, v93
	v_cndmask_b32_e32 v100, v100, v249, vcc
	v_alignbit_b32 v101, v92, v92, 16
	v_bfi_b32 v249, s5, v93, v92
	v_cndmask_b32_e32 v101, v101, v249, vcc
	s_nop 1
	v_mfma_f32_32x32x16_bf16 v[50:65], v[98:101], v[102:105], v[50:65]
	v_mfma_f32_32x32x16_bf16 v[34:49], v[98:101], v[106:109], v[34:49]
	v_mfma_f32_32x32x16_bf16 v[18:33], v[98:101], v[236:239], v[18:33]
	v_mfma_f32_32x32x16_bf16 v[2:17], v[98:101], v[240:243], v[2:17]
	ds_read2_b32 v[92:93], v245 offset1:1
	ds_read2_b32 v[94:95], v245 offset0:2 offset1:3
	ds_read_b32 v96, v245 offset:16
	ds_read_b128 v[102:105], v247 offset:0
	ds_read_b128 v[106:109], v247 offset:2560
	ds_read_b128 v[236:239], v247 offset:5120
	ds_read_b128 v[240:243], v247 offset:7680
	v_add_u32_e32 v245, 64, v245
	v_add_u32_e32 v247, 0xffffffb0, v247
	s_add_i32 s4, s4, -1
	s_cmp_lg_u32 s4, 0
	s_cbranch_scc1 .Lhy_seg3
	s_waitcnt lgkmcnt(7)
	v_alignbit_b32 v72, v69, v69, 16
	v_bfi_b32 v249, s5, v70, v69
	v_cndmask_b32_e32 v72, v72, v249, vcc
	v_alignbit_b32 v73, v68, v68, 16
	v_bfi_b32 v249, s5, v69, v68
	v_cndmask_b32_e32 v73, v73, v249, vcc
	v_alignbit_b32 v74, v67, v67, 16
	v_bfi_b32 v249, s5, v68, v67
	v_cndmask_b32_e32 v74, v74, v249, vcc
	v_alignbit_b32 v75, v66, v66, 16
	v_bfi_b32 v249, s5, v67, v66
	v_cndmask_b32_e32 v75, v75, v249, vcc
	s_nop 1
	v_mfma_f32_32x32x16_bf16 v[50:65], v[72:75], v[76:79], v[50:65]
	v_mfma_f32_32x32x16_bf16 v[34:49], v[72:75], v[80:83], v[34:49]
	v_mfma_f32_32x32x16_bf16 v[18:33], v[72:75], v[84:87], v[18:33]
	v_mfma_f32_32x32x16_bf16 v[2:17], v[72:75], v[88:91], v[2:17]
	s_waitcnt lgkmcnt(0)
	v_alignbit_b32 v98, v95, v95, 16
	v_bfi_b32 v249, s5, v96, v95
	v_cndmask_b32_e32 v98, v98, v249, vcc
	v_alignbit_b32 v99, v94, v94, 16
	v_bfi_b32 v249, s5, v95, v94
	v_cndmask_b32_e32 v99, v99, v249, vcc
	v_alignbit_b32 v100, v93, v93, 16
	v_bfi_b32 v249, s5, v94, v93
	v_cndmask_b32_e32 v100, v100, v249, vcc
	v_alignbit_b32 v101, v92, v92, 16
	v_bfi_b32 v249, s5, v93, v92
	v_cndmask_b32_e32 v101, v101, v249, vcc
	s_nop 1
	v_mfma_f32_32x32x16_bf16 v[50:65], v[98:101], v[102:105], v[50:65]
	v_mfma_f32_32x32x16_bf16 v[34:49], v[98:101], v[106:109], v[34:49]
	v_mfma_f32_32x32x16_bf16 v[18:33], v[98:101], v[236:239], v[18:33]
	v_mfma_f32_32x32x16_bf16 v[2:17], v[98:101], v[240:243], v[2:17]
	ds_read2_b32 v[66:67], v244 offset1:1
	ds_read2_b32 v[68:69], v244 offset0:2 offset1:3
	ds_read_b32 v70, v244 offset:16
	ds_read_b128 v[80:83], v246 offset:2560
	ds_read_b128 v[84:87], v246 offset:5120
	ds_read_b128 v[88:91], v246 offset:7680
	v_add_u32_e32 v244, 64, v244
	v_add_u32_e32 v246, 0xffffffb0, v246
	ds_read2_b32 v[92:93], v245 offset1:1
	ds_read2_b32 v[94:95], v245 offset0:2 offset1:3
	ds_read_b32 v96, v245 offset:16
	ds_read_b128 v[106:109], v247 offset:2560
	ds_read_b128 v[236:239], v247 offset:5120
	ds_read_b128 v[240:243], v247 offset:7680
	v_add_u32_e32 v245, 64, v245
	v_add_u32_e32 v247, 0xffffffb0, v247
	s_mov_b32 s4, 31
.Lhy_seg4:
	s_waitcnt lgkmcnt(6)
	v_alignbit_b32 v72, v69, v69, 16
	v_bfi_b32 v249, s5, v70, v69
	v_cndmask_b32_e32 v72, v72, v249, vcc
	v_alignbit_b32 v73, v68, v68, 16
	v_bfi_b32 v249, s5, v69, v68
	v_cndmask_b32_e32 v73, v73, v249, vcc
	v_alignbit_b32 v74, v67, v67, 16
	v_bfi_b32 v249, s5, v68, v67
	v_cndmask_b32_e32 v74, v74, v249, vcc
	v_alignbit_b32 v75, v66, v66, 16
	v_bfi_b32 v249, s5, v67, v66
	v_cndmask_b32_e32 v75, v75, v249, vcc
	s_nop 1
	v_mfma_f32_32x32x16_bf16 v[34:49], v[72:75], v[80:83], v[34:49]
	v_mfma_f32_32x32x16_bf16 v[18:33], v[72:75], v[84:87], v[18:33]
	v_mfma_f32_32x32x16_bf16 v[2:17], v[72:75], v[88:91], v[2:17]
	ds_read2_b32 v[66:67], v244 offset1:1
	ds_read2_b32 v[68:69], v244 offset0:2 offset1:3
	ds_read_b32 v70, v244 offset:16
	ds_read_b128 v[80:83], v246 offset:2560
	ds_read_b128 v[84:87], v246 offset:5120
	ds_read_b128 v[88:91], v246 offset:7680
	v_add_u32_e32 v244, 64, v244
	v_add_u32_e32 v246, 0xffffffb0, v246
	s_waitcnt lgkmcnt(6)
	v_alignbit_b32 v98, v95, v95, 16
	v_bfi_b32 v249, s5, v96, v95
	v_cndmask_b32_e32 v98, v98, v249, vcc
	v_alignbit_b32 v99, v94, v94, 16
	v_bfi_b32 v249, s5, v95, v94
	v_cndmask_b32_e32 v99, v99, v249, vcc
	v_alignbit_b32 v100, v93, v93, 16
	v_bfi_b32 v249, s5, v94, v93
	v_cndmask_b32_e32 v100, v100, v249, vcc
	v_alignbit_b32 v101, v92, v92, 16
	v_bfi_b32 v249, s5, v93, v92
	v_cndmask_b32_e32 v101, v101, v249, vcc
	s_nop 1
	v_mfma_f32_32x32x16_bf16 v[34:49], v[98:101], v[106:109], v[34:49]
	v_mfma_f32_32x32x16_bf16 v[18:33], v[98:101], v[236:239], v[18:33]
	v_mfma_f32_32x32x16_bf16 v[2:17], v[98:101], v[240:243], v[2:17]
	ds_read2_b32 v[92:93], v245 offset1:1
	ds_read2_b32 v[94:95], v245 offset0:2 offset1:3
	ds_read_b32 v96, v245 offset:16
	ds_read_b128 v[106:109], v247 offset:2560
	ds_read_b128 v[236:239], v247 offset:5120
	ds_read_b128 v[240:243], v247 offset:7680
	v_add_u32_e32 v245, 64, v245
	v_add_u32_e32 v247, 0xffffffb0, v247
	s_add_i32 s4, s4, -1
	s_cmp_lg_u32 s4, 0
	s_cbranch_scc1 .Lhy_seg4
	s_waitcnt lgkmcnt(6)
	v_alignbit_b32 v72, v69, v69, 16
	v_bfi_b32 v249, s5, v70, v69
	v_cndmask_b32_e32 v72, v72, v249, vcc
	v_alignbit_b32 v73, v68, v68, 16
	v_bfi_b32 v249, s5, v69, v68
	v_cndmask_b32_e32 v73, v73, v249, vcc
	v_alignbit_b32 v74, v67, v67, 16
	v_bfi_b32 v249, s5, v68, v67
	v_cndmask_b32_e32 v74, v74, v249, vcc
	v_alignbit_b32 v75, v66, v66, 16
	v_bfi_b32 v249, s5, v67, v66
	v_cndmask_b32_e32 v75, v75, v249, vcc
	s_nop 1
	v_mfma_f32_32x32x16_bf16 v[34:49], v[72:75], v[80:83], v[34:49]
	v_mfma_f32_32x32x16_bf16 v[18:33], v[72:75], v[84:87], v[18:33]
	v_mfma_f32_32x32x16_bf16 v[2:17], v[72:75], v[88:91], v[2:17]
	s_waitcnt lgkmcnt(0)
	v_alignbit_b32 v98, v95, v95, 16
	v_bfi_b32 v249, s5, v96, v95
	v_cndmask_b32_e32 v98, v98, v249, vcc
	v_alignbit_b32 v99, v94, v94, 16
	v_bfi_b32 v249, s5, v95, v94
	v_cndmask_b32_e32 v99, v99, v249, vcc
	v_alignbit_b32 v100, v93, v93, 16
	v_bfi_b32 v249, s5, v94, v93
	v_cndmask_b32_e32 v100, v100, v249, vcc
	v_alignbit_b32 v101, v92, v92, 16
	v_bfi_b32 v249, s5, v93, v92
	v_cndmask_b32_e32 v101, v101, v249, vcc
	s_nop 1
	v_mfma_f32_32x32x16_bf16 v[34:49], v[98:101], v[106:109], v[34:49]
	v_mfma_f32_32x32x16_bf16 v[18:33], v[98:101], v[236:239], v[18:33]
	v_mfma_f32_32x32x16_bf16 v[2:17], v[98:101], v[240:243], v[2:17]
	ds_read2_b32 v[66:67], v244 offset1:1
	ds_read2_b32 v[68:69], v244 offset0:2 offset1:3
	ds_read_b32 v70, v244 offset:16
	ds_read_b128 v[84:87], v246 offset:5120
	ds_read_b128 v[88:91], v246 offset:7680
	v_add_u32_e32 v244, 64, v244
	v_add_u32_e32 v246, 0xffffffb0, v246
	ds_read2_b32 v[92:93], v245 offset1:1
	ds_read2_b32 v[94:95], v245 offset0:2 offset1:3
	ds_read_b32 v96, v245 offset:16
	ds_read_b128 v[236:239], v247 offset:5120
	ds_read_b128 v[240:243], v247 offset:7680
	v_add_u32_e32 v245, 64, v245
	v_add_u32_e32 v247, 0xffffffb0, v247
	s_mov_b32 s4, 31
.Lhy_seg5:
	s_waitcnt lgkmcnt(5)
	v_alignbit_b32 v72, v69, v69, 16
	v_bfi_b32 v249, s5, v70, v69
	v_cndmask_b32_e32 v72, v72, v249, vcc
	v_alignbit_b32 v73, v68, v68, 16
	v_bfi_b32 v249, s5, v69, v68
	v_cndmask_b32_e32 v73, v73, v249, vcc
	v_alignbit_b32 v74, v67, v67, 16
	v_bfi_b32 v249, s5, v68, v67
	v_cndmask_b32_e32 v74, v74, v249, vcc
	v_alignbit_b32 v75, v66, v66, 16
	v_bfi_b32 v249, s5, v67, v66
	v_cndmask_b32_e32 v75, v75, v249, vcc
	s_nop 1
	v_mfma_f32_32x32x16_bf16 v[18:33], v[72:75], v[84:87], v[18:33]
	v_mfma_f32_32x32x16_bf16 v[2:17], v[72:75], v[88:91], v[2:17]
	ds_read2_b32 v[66:67], v244 offset1:1
	ds_read2_b32 v[68:69], v244 offset0:2 offset1:3
	ds_read_b32 v70, v244 offset:16
	ds_read_b128 v[84:87], v246 offset:5120
	ds_read_b128 v[88:91], v246 offset:7680
	v_add_u32_e32 v244, 64, v244
	v_add_u32_e32 v246, 0xffffffb0, v246
	s_waitcnt lgkmcnt(5)
	v_alignbit_b32 v98, v95, v95, 16
	v_bfi_b32 v249, s5, v96, v95
	v_cndmask_b32_e32 v98, v98, v249, vcc
	v_alignbit_b32 v99, v94, v94, 16
	v_bfi_b32 v249, s5, v95, v94
	v_cndmask_b32_e32 v99, v99, v249, vcc
	v_alignbit_b32 v100, v93, v93, 16
	v_bfi_b32 v249, s5, v94, v93
	v_cndmask_b32_e32 v100, v100, v249, vcc
	v_alignbit_b32 v101, v92, v92, 16
	v_bfi_b32 v249, s5, v93, v92
	v_cndmask_b32_e32 v101, v101, v249, vcc
	s_nop 1
	v_mfma_f32_32x32x16_bf16 v[18:33], v[98:101], v[236:239], v[18:33]
	v_mfma_f32_32x32x16_bf16 v[2:17], v[98:101], v[240:243], v[2:17]
	ds_read2_b32 v[92:93], v245 offset1:1
	ds_read2_b32 v[94:95], v245 offset0:2 offset1:3
	ds_read_b32 v96, v245 offset:16
	ds_read_b128 v[236:239], v247 offset:5120
	ds_read_b128 v[240:243], v247 offset:7680
	v_add_u32_e32 v245, 64, v245
	v_add_u32_e32 v247, 0xffffffb0, v247
	s_add_i32 s4, s4, -1
	s_cmp_lg_u32 s4, 0
	s_cbranch_scc1 .Lhy_seg5
	s_waitcnt lgkmcnt(5)
	v_alignbit_b32 v72, v69, v69, 16
	v_bfi_b32 v249, s5, v70, v69
	v_cndmask_b32_e32 v72, v72, v249, vcc
	v_alignbit_b32 v73, v68, v68, 16
	v_bfi_b32 v249, s5, v69, v68
	v_cndmask_b32_e32 v73, v73, v249, vcc
	v_alignbit_b32 v74, v67, v67, 16
	v_bfi_b32 v249, s5, v68, v67
	v_cndmask_b32_e32 v74, v74, v249, vcc
	v_alignbit_b32 v75, v66, v66, 16
	v_bfi_b32 v249, s5, v67, v66
	v_cndmask_b32_e32 v75, v75, v249, vcc
	s_nop 1
	v_mfma_f32_32x32x16_bf16 v[18:33], v[72:75], v[84:87], v[18:33]
	v_mfma_f32_32x32x16_bf16 v[2:17], v[72:75], v[88:91], v[2:17]
	s_waitcnt lgkmcnt(0)
	v_alignbit_b32 v98, v95, v95, 16
	v_bfi_b32 v249, s5, v96, v95
	v_cndmask_b32_e32 v98, v98, v249, vcc
	v_alignbit_b32 v99, v94, v94, 16
	v_bfi_b32 v249, s5, v95, v94
	v_cndmask_b32_e32 v99, v99, v249, vcc
	v_alignbit_b32 v100, v93, v93, 16
	v_bfi_b32 v249, s5, v94, v93
	v_cndmask_b32_e32 v100, v100, v249, vcc
	v_alignbit_b32 v101, v92, v92, 16
	v_bfi_b32 v249, s5, v93, v92
	v_cndmask_b32_e32 v101, v101, v249, vcc
	s_nop 1
	v_mfma_f32_32x32x16_bf16 v[18:33], v[98:101], v[236:239], v[18:33]
	v_mfma_f32_32x32x16_bf16 v[2:17], v[98:101], v[240:243], v[2:17]
	ds_read2_b32 v[66:67], v244 offset1:1
	ds_read2_b32 v[68:69], v244 offset0:2 offset1:3
	ds_read_b32 v70, v244 offset:16
	ds_read_b128 v[88:91], v246 offset:7680
	v_add_u32_e32 v244, 64, v244
	v_add_u32_e32 v246, 0xffffffb0, v246
	ds_read2_b32 v[92:93], v245 offset1:1
	ds_read2_b32 v[94:95], v245 offset0:2 offset1:3
	ds_read_b32 v96, v245 offset:16
	ds_read_b128 v[240:243], v247 offset:7680
	v_add_u32_e32 v245, 64, v245
	v_add_u32_e32 v247, 0xffffffb0, v247
	s_mov_b32 s4, 31
.Lhy_seg6:
	s_waitcnt lgkmcnt(4)
	v_alignbit_b32 v72, v69, v69, 16
	v_bfi_b32 v249, s5, v70, v69
	v_cndmask_b32_e32 v72, v72, v249, vcc
	v_alignbit_b32 v73, v68, v68, 16
	v_bfi_b32 v249, s5, v69, v68
	v_cndmask_b32_e32 v73, v73, v249, vcc
	v_alignbit_b32 v74, v67, v67, 16
	v_bfi_b32 v249, s5, v68, v67
	v_cndmask_b32_e32 v74, v74, v249, vcc
	v_alignbit_b32 v75, v66, v66, 16
	v_bfi_b32 v249, s5, v67, v66
	v_cndmask_b32_e32 v75, v75, v249, vcc
	s_nop 1
	v_mfma_f32_32x32x16_bf16 v[2:17], v[72:75], v[88:91], v[2:17]
	ds_read2_b32 v[66:67], v244 offset1:1
	ds_read2_b32 v[68:69], v244 offset0:2 offset1:3
	ds_read_b32 v70, v244 offset:16
	ds_read_b128 v[88:91], v246 offset:7680
	v_add_u32_e32 v244, 64, v244
	v_add_u32_e32 v246, 0xffffffb0, v246
	s_waitcnt lgkmcnt(4)
	v_alignbit_b32 v98, v95, v95, 16
	v_bfi_b32 v249, s5, v96, v95
	v_cndmask_b32_e32 v98, v98, v249, vcc
	v_alignbit_b32 v99, v94, v94, 16
	v_bfi_b32 v249, s5, v95, v94
	v_cndmask_b32_e32 v99, v99, v249, vcc
	v_alignbit_b32 v100, v93, v93, 16
	v_bfi_b32 v249, s5, v94, v93
	v_cndmask_b32_e32 v100, v100, v249, vcc
	v_alignbit_b32 v101, v92, v92, 16
	v_bfi_b32 v249, s5, v93, v92
	v_cndmask_b32_e32 v101, v101, v249, vcc
	s_nop 1
	v_mfma_f32_32x32x16_bf16 v[2:17], v[98:101], v[240:243], v[2:17]
	ds_read2_b32 v[92:93], v245 offset1:1
	ds_read2_b32 v[94:95], v245 offset0:2 offset1:3
	ds_read_b32 v96, v245 offset:16
	ds_read_b128 v[240:243], v247 offset:7680
	v_add_u32_e32 v245, 64, v245
	v_add_u32_e32 v247, 0xffffffb0, v247
	s_add_i32 s4, s4, -1
	s_cmp_lg_u32 s4, 0
	s_cbranch_scc1 .Lhy_seg6
	s_waitcnt lgkmcnt(4)
	v_alignbit_b32 v72, v69, v69, 16
	v_bfi_b32 v249, s5, v70, v69
	v_cndmask_b32_e32 v72, v72, v249, vcc
	v_alignbit_b32 v73, v68, v68, 16
	v_bfi_b32 v249, s5, v69, v68
	v_cndmask_b32_e32 v73, v73, v249, vcc
	v_alignbit_b32 v74, v67, v67, 16
	v_bfi_b32 v249, s5, v68, v67
	v_cndmask_b32_e32 v74, v74, v249, vcc
	v_alignbit_b32 v75, v66, v66, 16
	v_bfi_b32 v249, s5, v67, v66
	v_cndmask_b32_e32 v75, v75, v249, vcc
	s_nop 1
	v_mfma_f32_32x32x16_bf16 v[2:17], v[72:75], v[88:91], v[2:17]
	s_waitcnt lgkmcnt(0)
	v_alignbit_b32 v98, v95, v95, 16
	v_bfi_b32 v249, s5, v96, v95
	v_cndmask_b32_e32 v98, v98, v249, vcc
	v_alignbit_b32 v99, v94, v94, 16
	v_bfi_b32 v249, s5, v95, v94
	v_cndmask_b32_e32 v99, v99, v249, vcc
	v_alignbit_b32 v100, v93, v93, 16
	v_bfi_b32 v249, s5, v94, v93
	v_cndmask_b32_e32 v100, v100, v249, vcc
	v_alignbit_b32 v101, v92, v92, 16
	v_bfi_b32 v249, s5, v93, v92
	v_cndmask_b32_e32 v101, v101, v249, vcc
	s_nop 1
	v_mfma_f32_32x32x16_bf16 v[2:17], v[98:101], v[240:243], v[2:17]
	s_nop 7
